# SB attention: V^T tile loads widened from 8x dwordx2 to 4x dwordx4 with v_permlane32_swap to rebuild the MFMA fragment (halves cache-line touches); bit-identical
# speedup vs baseline: 1.0142x; 1.0142x over previous
.LBB0_140:
	s_ashr_i32 s44, s49, 3
	s_lshl_b32 s39, s49, 2
	s_and_b32 s38, s44, 0x1ffffe0
	s_and_b32 s40, s39, 16
	s_or_b32 s38, s38, s40
	s_lshl_b32 s42, s38, 7
	s_lshl_b32 s38, s49, 5
	s_and_b32 s38, s38, 0x700
	v_add_u32_e32 v160, s38, v111
	s_bfe_u32 s40, s49, 0x20006
	s_and_b32 s39, s39, 12
	v_add_u32_e32 v0, s42, v160
	s_or_b32 s45, s39, s40
	v_or_b32_e32 v88, v0, v110
	v_ashrrev_i32_e32 v87, 5, v160
	v_mov_b32_e32 v15, 0
	v_ashrrev_i32_e32 v89, 31, v88
	s_lshl_b32 s50, s45, 6
	v_cmp_lt_i32_e64 s[38:39], -1, v87
	v_mov_b32_e32 v14, v15
	v_mov_b32_e32 v13, v15
	v_mov_b32_e32 v12, v15
	v_mov_b32_e32 v11, v15
	v_mov_b32_e32 v10, v15
	v_mov_b32_e32 v9, v15
	v_mov_b32_e32 v8, v15
	v_mov_b32_e32 v7, v15
	s_waitcnt lgkmcnt(1)
	v_mov_b32_e32 v6, v15
	s_waitcnt lgkmcnt(0)
	v_mov_b32_e32 v5, v15
	v_mov_b32_e32 v4, v15
	v_mov_b32_e32 v3, v15
	v_mov_b32_e32 v2, v15
	v_mov_b32_e32 v1, v15
	v_mov_b32_e32 v0, v15
	v_mov_b32_e32 v31, v15
	v_mov_b32_e32 v30, v15
	v_mov_b32_e32 v29, v15
	v_mov_b32_e32 v28, v15
	v_mov_b32_e32 v27, v15
	v_mov_b32_e32 v26, v15
	v_mov_b32_e32 v25, v15
	v_mov_b32_e32 v24, v15
	v_mov_b32_e32 v23, v15
	v_mov_b32_e32 v22, v15
	v_mov_b32_e32 v21, v15
	v_mov_b32_e32 v20, v15
	v_mov_b32_e32 v19, v15
	v_mov_b32_e32 v18, v15
	v_mov_b32_e32 v17, v15
	v_mov_b32_e32 v16, v15
	s_and_saveexec_b64 s[40:41], s[38:39]
	s_cbranch_execz .LBB0_139
	v_readlane_b32 s38, v254, 10
	v_lshlrev_b64 v[0:1], 12, v[88:89]
	v_readlane_b32 s39, v254, 11
	s_lshl_b32 s92, s50, 1
	v_mov_b32_e32 v85, v161
	v_lshl_add_u64 v[0:1], s[38:39], 0, v[0:1]
	v_lshl_add_u64 v[0:1], v[0:1], 0, s[92:93]
	v_lshl_add_u64 v[0:1], v[0:1], 0, v[84:85]
	global_load_dwordx4 v[48:51], v[0:1], off
	global_load_dwordx4 v[52:55], v[0:1], off offset:32
	global_load_dwordx4 v[56:59], v[0:1], off offset:64
	global_load_dwordx4 v[60:63], v[0:1], off offset:96
	s_and_b32 s38, s3, 0x700
	v_and_b32_e32 v3, 64, v205
	v_add_u32_e32 v85, s38, v111
	s_lshl_b32 s38, s47, 7
	v_xor_b32_e32 v2, 32, v205
	v_add_u32_e32 v3, 64, v3
	s_and_b32 s51, s38, 0x800
	v_cmp_lt_i32_e64 s[38:39], v2, v3
	s_ashr_i32 s43, s42, 31
	v_lshl_add_u64 v[0:1], s[42:43], 1, v[80:81]
	v_cndmask_b32_e64 v2, v205, v2, s[38:39]
	s_lshl_b32 s38, s44, 7
	v_lshlrev_b32_e32 v113, 2, v2
	v_lshl_or_b32 v2, s45, 21, v112
	v_add_u32_e32 v2, v2, v86
	v_mov_b32_e32 v3, v161
	s_and_b32 s38, s38, 0xfffff000
	v_lshl_add_u64 v[90:91], v[0:1], 0, v[2:3]
	v_or_b32_e32 v0, s38, v110
	v_or_b32_e32 v114, s51, v0
	v_mov_b32_e32 v0, 0
	v_lshl_add_u64 v[92:93], v[82:83], 0, s[92:93]
	v_mov_b32_e32 v115, 1.0
	s_mov_b64 s[42:43], 0
	v_mov_b32_e32 v1, v0
	v_mov_b32_e32 v2, v0
	v_mov_b32_e32 v3, v0
	v_mov_b32_e32 v4, v0
	v_mov_b32_e32 v5, v0
	v_mov_b32_e32 v6, v0
	v_mov_b32_e32 v7, v0
	v_mov_b32_e32 v8, v0
	v_mov_b32_e32 v9, v0
	v_mov_b32_e32 v10, v0
	v_mov_b32_e32 v11, v0
	v_mov_b32_e32 v12, v0
	v_mov_b32_e32 v13, v0
	v_mov_b32_e32 v14, v0
	v_mov_b32_e32 v15, v0
	v_mov_b32_e32 v16, v0
	v_mov_b32_e32 v17, v0
	v_mov_b32_e32 v18, v0
	v_mov_b32_e32 v19, v0
	v_mov_b32_e32 v20, v0
	v_mov_b32_e32 v21, v0
	v_mov_b32_e32 v22, v0
	v_mov_b32_e32 v23, v0
	v_mov_b32_e32 v24, v0
	v_mov_b32_e32 v25, v0
	v_mov_b32_e32 v26, v0
	v_mov_b32_e32 v27, v0
	v_mov_b32_e32 v28, v0
	v_mov_b32_e32 v29, v0
	v_mov_b32_e32 v30, v0
	v_mov_b32_e32 v31, v0
	s_branch .LBB0_143
.LBB0_142:
	s_or_b64 exec, exec, s[44:45]
	v_mov_b32_e32 v108, v35
	v_mov_b32_e32 v32, v34
	v_mov_b32_e32 v106, v103
	v_mov_b32_e32 v38, v102
	v_pk_mul_f32 v[108:109], v[108:109], v[32:33]
	v_pk_mul_f32 v[106:107], v[106:107], v[38:39]
	v_mov_b32_e32 v125, v108
	v_mov_b32_e32 v124, v106
	v_mov_b32_e32 v108, v107
	v_pk_mul_f32 v[124:125], v[124:125], v[108:109]
	v_mov_b32_e32 v104, v97
	v_mov_b32_e32 v40, v96
	ds_bpermute_b32 v127, v113, v125
	ds_bpermute_b32 v126, v113, v124
	v_pk_mul_f32 v[104:105], v[104:105], v[40:41]
	v_mov_b32_e32 v100, v47
	v_pk_mul_f32 v[128:129], v[104:105], v[104:105] op_sel:[0,1] op_sel_hi:[1,0]
	ds_bpermute_b32 v102, v113, v128
	v_mov_b32_e32 v42, v46
	s_waitcnt lgkmcnt(1)
	v_pk_mul_f32 v[124:125], v[124:125], v[126:127]
	v_pk_mul_f32 v[100:101], v[100:101], v[42:43]
	v_mul_f32_e32 v106, v103, v107
	v_mov_b32_e32 v129, v124
	v_mov_b32_e32 v103, v125
	v_mul_f32_e32 v96, v100, v101
	ds_bpermute_b32 v132, v113, v96
	v_mul_f32_e32 v34, v115, v125
	s_waitcnt lgkmcnt(1)
	v_pk_mul_f32 v[124:125], v[128:129], v[102:103]
	v_mul_f32_e32 v32, v124, v125
	v_mul_f32_e32 v32, v115, v32
	v_mul_f32_e32 v100, v47, v101
	v_mul_f32_e32 v40, v115, v125
	s_waitcnt lgkmcnt(0)
	v_cndmask_b32_e32 v46, 1.0, v132, vcc
	v_mul_f32_e32 v32, v46, v32
	v_cndmask_b32_e32 v42, 1.0, v102, vcc
	v_pk_mul_f32 v[46:47], v[100:101], v[32:33] op_sel_hi:[1,0]
	v_mul_f32_e32 v104, v97, v105
	v_pk_mul_f32 v[46:47], v[98:99], v[46:47]
	v_mul_f32_e32 v43, v43, v32
	v_mul_f32_e32 v98, v122, v32
	v_mul_f32_e32 v32, v42, v40
	v_cndmask_b32_e32 v38, 1.0, v126, vcc
	v_mul_f32_e32 v97, v123, v43
	v_pk_mul_f32 v[42:43], v[104:105], v[32:33] op_sel_hi:[1,0]
	v_mul_f32_e32 v40, v41, v32
	v_pk_mul_f32 v[42:43], v[94:95], v[42:43]
	v_mul_f32_e32 v95, v121, v32
	v_mul_f32_e32 v32, v38, v34
	v_mul_f32_e32 v94, v120, v40
	v_pk_mul_f32 v[40:41], v[106:107], v[32:33] op_sel_hi:[1,0]
	v_mul_f32_e32 v34, v39, v32
	v_pk_mul_f32 v[44:45], v[44:45], v[40:41]
	v_cvt_pk_bf16_f32 v38, v46, v47
	v_cvt_pk_bf16_f32 v39, v97, v98
	v_cvt_pk_bf16_f32 v40, v42, v43
	v_cvt_pk_bf16_f32 v41, v94, v95
	s_waitcnt vmcnt(3)
	v_permlane32_swap_b32_e32 v72, v74
	v_permlane32_swap_b32_e32 v73, v75
	v_mul_f32_e32 v43, v119, v32
	v_cndmask_b32_e32 v32, 1.0, v127, vcc
	v_mfma_f32_32x32x16_bf16 v[0:15], v[72:75], v[38:41], v[0:15]
	v_mul_f32_e32 v32, v115, v32
	v_mul_f32_e32 v108, v35, v109
	v_mul_f32_e32 v42, v118, v34
	v_mul_f32_e64 v34, v108, v32
	v_mul_f32_e64 v35, v109, v32
	v_mul_f32_e32 v33, v33, v32
	v_pk_mul_f32 v[34:35], v[36:37], v[34:35]
	v_mul_f32_e32 v36, v116, v33
	s_waitcnt vmcnt(1)
	v_permlane32_swap_b32_e32 v76, v78
	v_permlane32_swap_b32_e32 v77, v79
	v_permlane32_swap_b32_e32 v64, v66
	v_permlane32_swap_b32_e32 v65, v67
	v_mfma_f32_32x32x16_bf16 v[16:31], v[76:79], v[38:41], v[16:31]
	v_mul_f32_e32 v37, v117, v32
	v_cvt_pk_bf16_f32 v34, v34, v35
	v_cvt_pk_bf16_f32 v35, v36, v37
	v_mul_f32_e32 v36, v96, v132
	v_cvt_pk_bf16_f32 v32, v44, v45
	v_cvt_pk_bf16_f32 v33, v42, v43
	v_mul_f32_e32 v36, v124, v36
	v_mul_f32_e32 v36, v36, v125
	v_mfma_f32_32x32x16_bf16 v[0:15], v[64:67], v[32:35], v[0:15]
	v_mul_f32_e32 v115, v115, v36
	s_mov_b32 s38, 0x2081cea
	v_cmp_gt_f32_e64 s[38:39], s38, v115
	s_cmp_eq_u64 s[38:39], exec
	v_add_co_u32_e64 v87, s[38:39], -1, v87
	s_cselect_b64 s[44:45], -1, 0
	s_waitcnt vmcnt(0)
	v_permlane32_swap_b32_e32 v68, v70
	v_permlane32_swap_b32_e32 v69, v71
	s_nop 1
	v_mfma_f32_32x32x16_bf16 v[16:31], v[68:71], v[32:35], v[16:31]
	s_xor_b64 s[38:39], s[38:39], -1
	s_or_b64 s[38:39], s[38:39], s[44:45]
	s_and_b64 s[38:39], exec, s[38:39]
	s_or_b64 s[42:43], s[38:39], s[42:43]
	v_subrev_u32_e32 v160, 32, v160
	s_andn2_b64 exec, exec, s[42:43]
	s_cbranch_execz .LBB0_138
.LBB0_143:
	v_add_u32_e32 v32, v114, v160
	v_ashrrev_i32_e32 v33, 31, v32
	v_lshlrev_b64 v[32:33], 12, v[32:33]
	v_lshl_add_u64 v[72:73], v[92:93], 0, v[32:33]
	global_load_dwordx4 v[32:35], v[72:73], off offset:2048
	global_load_dwordx4 v[64:67], v[72:73], off offset:2080
	global_load_dwordx4 v[68:71], v[72:73], off offset:2112
	global_load_dwordx4 v[94:97], v[72:73], off offset:2144
	v_lshl_add_u64 v[76:77], v[160:161], 1, v[90:91]
	s_mov_b32 s38, 0x100000
	s_waitcnt vmcnt(3)
	v_mfma_f32_32x32x16_bf16 v[32:47], v[32:35], v[48:51], 0
	s_waitcnt vmcnt(2)
	v_mfma_f32_32x32x16_bf16 v[32:47], v[64:67], v[52:55], v[32:47]
	global_load_dwordx4 v[72:75], v[76:77], off
	global_load_dwordx4 v[64:67], v[76:77], off offset:32
	s_waitcnt vmcnt(3)
	v_mfma_f32_32x32x16_bf16 v[32:47], v[68:71], v[56:59], v[32:47]
	v_add_co_u32_e64 v70, s[38:39], s38, v76
	s_nop 1
	v_addc_co_u32_e64 v71, s[38:39], 0, v77, s[38:39]
	global_load_dwordx4 v[76:79], v[70:71], off
	global_load_dwordx4 v[68:71], v[70:71], off offset:32
	v_cmp_eq_u32_e64 s[38:39], v85, v160
	s_waitcnt vmcnt(4)
	v_mfma_f32_32x32x16_bf16 v[32:47], v[94:97], v[60:63], v[32:47]
	s_nop 11
	v_exp_f32_e32 v32, v32
	v_exp_f32_e32 v33, v33
	v_exp_f32_e32 v34, v34
	v_exp_f32_e32 v35, v35
	v_exp_f32_e32 v94, v36
	v_exp_f32_e32 v95, v37
	v_exp_f32_e32 v38, v38
	v_exp_f32_e32 v39, v39
	v_exp_f32_e32 v40, v40
	v_exp_f32_e32 v41, v41
	v_exp_f32_e32 v42, v42
	v_exp_f32_e32 v43, v43
	v_exp_f32_e32 v96, v44
	v_exp_f32_e32 v97, v45
	v_exp_f32_e32 v46, v46
	v_exp_f32_e32 v47, v47
	v_min_f32_e32 v36, 0x7149f2ca, v32
	v_min_f32_e32 v37, 0x7149f2ca, v33
	v_min_f32_e32 v32, 0x7149f2ca, v34
	v_min_f32_e32 v100, 0x7149f2ca, v35
	v_min_f32_e32 v44, 0x7149f2ca, v94
	v_min_f32_e32 v45, 0x7149f2ca, v95
	v_min_f32_e32 v38, 0x7149f2ca, v38
	v_min_f32_e32 v104, 0x7149f2ca, v39
	v_min_f32_e32 v116, 0x7149f2ca, v40
	v_min_f32_e32 v117, 0x7149f2ca, v41
	v_min_f32_e32 v40, 0x7149f2ca, v42
	v_min_f32_e32 v42, 0x7149f2ca, v43
	v_min_f32_e32 v124, 0x7149f2ca, v96
	v_min_f32_e32 v125, 0x7149f2ca, v97
	v_min_f32_e32 v106, 0x7149f2ca, v46
	v_min_f32_e32 v108, 0x7149f2ca, v47
	v_add_f32_e32 v33, 1.0, v36
	v_add_f32_e32 v34, 1.0, v37
	v_add_f32_e32 v35, 1.0, v32
	v_add_f32_e32 v39, 1.0, v100
	v_add_f32_e32 v41, 1.0, v44
	v_add_f32_e32 v94, 1.0, v45
	v_add_f32_e32 v95, 1.0, v38
	v_add_f32_e32 v98, 1.0, v104
	v_add_f32_e32 v99, 1.0, v116
	v_add_f32_e32 v103, 1.0, v117
	v_add_f32_e32 v107, 1.0, v40
	v_add_f32_e32 v109, 1.0, v42
	v_add_f32_e32 v118, 1.0, v124
	v_add_f32_e32 v119, 1.0, v125
	v_add_f32_e32 v120, 1.0, v106
	v_add_f32_e32 v121, 1.0, v108
	v_rcp_f32_e32 v46, v33
	v_rcp_f32_e32 v47, v34
	v_rcp_f32_e32 v101, v35
	v_rcp_f32_e32 v43, v39
	v_rcp_f32_e32 v96, v41
	v_rcp_f32_e32 v97, v94
	v_rcp_f32_e32 v105, v95
	v_rcp_f32_e32 v41, v98
	v_rcp_f32_e32 v102, v99
	v_rcp_f32_e32 v103, v103
	v_rcp_f32_e32 v107, v107
	v_rcp_f32_e32 v39, v109
	v_rcp_f32_e32 v34, v118
	v_rcp_f32_e32 v35, v119
	v_rcp_f32_e32 v109, v120
	v_rcp_f32_e32 v33, v121
	v_pk_mul_f32 v[98:99], v[36:37], v[46:47]
	v_mul_f32_e32 v123, v32, v101
	v_mul_f32_e32 v122, v100, v43
	v_pk_mul_f32 v[94:95], v[44:45], v[96:97]
	v_mul_f32_e32 v120, v38, v105
	v_mul_f32_e32 v121, v104, v41
	v_pk_mul_f32 v[44:45], v[116:117], v[102:103]
	v_mul_f32_e32 v118, v40, v107
	v_mul_f32_e32 v119, v42, v39
	v_pk_mul_f32 v[36:37], v[124:125], v[34:35]
	v_mul_f32_e32 v116, v106, v109
	v_mul_f32_e32 v117, v108, v33
	s_and_saveexec_b64 s[44:45], s[38:39]
	s_cbranch_execz .LBB0_142
	v_cndmask_b32_e64 v46, 1.0, v46, s[4:5]
	v_cndmask_b32_e64 v47, 1.0, v47, s[6:7]
	v_cndmask_b32_e64 v99, 0, v99, s[6:7]
	v_cndmask_b32_e64 v98, 0, v98, s[4:5]
	v_cndmask_b32_e64 v101, 1.0, v101, s[8:9]
	v_cndmask_b32_e64 v123, 0, v123, s[8:9]
	v_cndmask_b32_e64 v43, 1.0, v43, s[10:11]
	v_cndmask_b32_e64 v122, 0, v122, s[10:11]
	v_cndmask_b32_e64 v96, 1.0, v96, s[14:15]
	v_cndmask_b32_e64 v97, 1.0, v97, s[12:13]
	v_cndmask_b32_e64 v95, 0, v95, s[12:13]
	v_cndmask_b32_e64 v94, 0, v94, s[14:15]
	v_cndmask_b32_e64 v105, 1.0, v105, s[16:17]
	v_cndmask_b32_e64 v120, 0, v120, s[16:17]
	v_cndmask_b32_e64 v41, 1.0, v41, s[18:19]
	v_cndmask_b32_e64 v121, 0, v121, s[18:19]
	v_cndmask_b32_e64 v102, 1.0, v102, s[22:23]
	v_cndmask_b32_e64 v103, 1.0, v103, s[20:21]
	v_cndmask_b32_e64 v45, 0, v45, s[20:21]
	v_cndmask_b32_e64 v44, 0, v44, s[22:23]
	v_cndmask_b32_e64 v107, 1.0, v107, s[24:25]
	v_cndmask_b32_e64 v118, 0, v118, s[24:25]
	v_cndmask_b32_e64 v39, 1.0, v39, s[26:27]
	v_cndmask_b32_e64 v119, 0, v119, s[26:27]
	v_cndmask_b32_e64 v34, 1.0, v34, s[30:31]
	v_cndmask_b32_e64 v35, 1.0, v35, s[28:29]
	v_cndmask_b32_e64 v37, 0, v37, s[28:29]
	v_cndmask_b32_e64 v36, 0, v36, s[30:31]
	v_cndmask_b32_e64 v109, 1.0, v109, s[34:35]
	v_cndmask_b32_e64 v116, 0, v116, s[34:35]
	v_cndmask_b32_e64 v33, 1.0, v33, s[36:37]
	v_cndmask_b32_e64 v117, 0, v117, s[36:37]
	s_branch .LBB0_142
	s_nop 0
	s_nop 0
	s_nop 0
	s_nop 0
	s_nop 0
	s_nop 0
	s_nop 0
	s_nop 0
	s_nop 0
	s_nop 0
	s_nop 0
	s_nop 0
	s_nop 0
	s_nop 0
